# P4 epilogue: per-row rstd loaded at tile start (before the K loop) into registers the loop never touches; epilogue no longer stalls on vmcnt(0) before its first multiply
# baseline (speedup 1.0000x reference)
.LBB0_1166:
	s_lshl_b32 s58, s20, 8
	s_add_i32 s58, s58, s39
	v_add_u32_e32 v250, s58, v169
	v_ashrrev_i32_e32 v251, 31, v250
	v_lshl_add_u64 v[250:251], v[250:251], 2, s[2:3]
	global_load_dword v232, v[250:251], off
	global_load_dword v233, v[250:251], off offset:64
	global_load_dword v234, v[250:251], off offset:128
	global_load_dword v235, v[250:251], off offset:192
	global_load_dword v236, v[250:251], off offset:512
	global_load_dword v237, v[250:251], off offset:576
	global_load_dword v238, v[250:251], off offset:640
	global_load_dword v239, v[250:251], off offset:704
	s_ashr_i32 s15, s14, 31
	v_cmp_lt_i64_e32 vcc, s[16:17], v[132:133]
	s_lshl_b64 s[16:17], s[14:15], 20
	v_readlane_b32 s18, v254, 54
	v_readlane_b32 s19, v254, 55
	s_add_u32 s16, s18, s16
	s_addc_u32 s17, s19, s17
	s_and_b64 s[18:19], vcc, exec
	s_cselect_b32 s15, s17, s23
	s_cselect_b32 s49, s16, s22
	s_ashr_i32 s13, s12, 31
	s_lshl_b64 s[18:19], s[12:13], 20
	s_add_u32 s18, s29, s18
	s_addc_u32 s19, s30, s19
	s_and_b64 s[26:27], vcc, exec
	s_cselect_b32 s13, s19, s25
	s_cselect_b32 s50, s18, s24
	s_add_u32 s22, s22, 0x80080
	s_addc_u32 s23, s23, 0
	s_add_u32 s51, s24, 0x100
	v_mov_b32_e32 v0, 0
	s_addc_u32 s52, s25, 0
	s_mov_b32 s53, -2
	v_mov_b32_e32 v1, v0
	v_mov_b32_e32 v2, v0
	v_mov_b32_e32 v3, v0
	v_mov_b32_e32 v4, v0
	v_mov_b32_e32 v5, v0
	v_mov_b32_e32 v6, v0
	v_mov_b32_e32 v7, v0
	v_mov_b32_e32 v12, v0
	v_mov_b32_e32 v13, v0
	v_mov_b32_e32 v14, v0
	v_mov_b32_e32 v15, v0
	v_mov_b32_e32 v20, v0
	v_mov_b32_e32 v21, v0
	v_mov_b32_e32 v22, v0
	v_mov_b32_e32 v23, v0
	v_mov_b32_e32 v28, v0
	v_mov_b32_e32 v29, v0
	v_mov_b32_e32 v30, v0
	v_mov_b32_e32 v31, v0
	v_mov_b32_e32 v36, v0
	v_mov_b32_e32 v37, v0
	v_mov_b32_e32 v38, v0
	v_mov_b32_e32 v39, v0
	v_mov_b32_e32 v44, v0
	v_mov_b32_e32 v45, v0
	v_mov_b32_e32 v46, v0
	v_mov_b32_e32 v47, v0
	v_mov_b32_e32 v52, v0
	v_mov_b32_e32 v53, v0
	v_mov_b32_e32 v54, v0
	v_mov_b32_e32 v55, v0
	v_mov_b32_e32 v8, v0
	v_mov_b32_e32 v9, v0
	v_mov_b32_e32 v10, v0
	v_mov_b32_e32 v11, v0
	v_mov_b32_e32 v16, v0
	v_mov_b32_e32 v17, v0
	v_mov_b32_e32 v18, v0
	v_mov_b32_e32 v19, v0
	v_mov_b32_e32 v24, v0
	v_mov_b32_e32 v25, v0
	v_mov_b32_e32 v26, v0
	v_mov_b32_e32 v27, v0
	v_mov_b32_e32 v32, v0
	v_mov_b32_e32 v33, v0
	v_mov_b32_e32 v34, v0
	v_mov_b32_e32 v35, v0
	v_mov_b32_e32 v40, v0
	v_mov_b32_e32 v41, v0
	v_mov_b32_e32 v42, v0
	v_mov_b32_e32 v43, v0
	v_mov_b32_e32 v48, v0
	v_mov_b32_e32 v49, v0
	v_mov_b32_e32 v50, v0
	v_mov_b32_e32 v51, v0
	v_mov_b32_e32 v56, v0
	v_mov_b32_e32 v57, v0
	v_mov_b32_e32 v58, v0
	v_mov_b32_e32 v59, v0
	v_mov_b32_e32 v60, v0
	v_mov_b32_e32 v61, v0
	v_mov_b32_e32 v62, v0
	v_mov_b32_e32 v63, v0
	v_mov_b32_e32 v64, v0
	v_mov_b32_e32 v65, v0
	v_mov_b32_e32 v66, v0
	v_mov_b32_e32 v67, v0
	v_mov_b32_e32 v68, v0
	v_mov_b32_e32 v69, v0
	v_mov_b32_e32 v70, v0
	v_mov_b32_e32 v71, v0
	v_mov_b32_e32 v76, v0
	v_mov_b32_e32 v77, v0
	v_mov_b32_e32 v78, v0
	v_mov_b32_e32 v79, v0
	v_mov_b32_e32 v84, v0
	v_mov_b32_e32 v85, v0
	v_mov_b32_e32 v86, v0
	v_mov_b32_e32 v87, v0
	v_mov_b32_e32 v92, v0
	v_mov_b32_e32 v93, v0
	v_mov_b32_e32 v94, v0
	v_mov_b32_e32 v95, v0
	v_mov_b32_e32 v100, v0
	v_mov_b32_e32 v101, v0
	v_mov_b32_e32 v102, v0
	v_mov_b32_e32 v103, v0
	v_mov_b32_e32 v108, v0
	v_mov_b32_e32 v109, v0
	v_mov_b32_e32 v110, v0
	v_mov_b32_e32 v111, v0
	v_mov_b32_e32 v112, v0
	v_mov_b32_e32 v113, v0
	v_mov_b32_e32 v114, v0
	v_mov_b32_e32 v115, v0
	v_mov_b32_e32 v72, v0
	v_mov_b32_e32 v73, v0
	v_mov_b32_e32 v74, v0
	v_mov_b32_e32 v75, v0
	v_mov_b32_e32 v80, v0
	v_mov_b32_e32 v81, v0
	v_mov_b32_e32 v82, v0
	v_mov_b32_e32 v83, v0
	v_mov_b32_e32 v88, v0
	v_mov_b32_e32 v89, v0
	v_mov_b32_e32 v90, v0
	v_mov_b32_e32 v91, v0
	v_mov_b32_e32 v96, v0
	v_mov_b32_e32 v97, v0
	v_mov_b32_e32 v98, v0
	v_mov_b32_e32 v99, v0
	v_mov_b32_e32 v104, v0
	v_mov_b32_e32 v105, v0
	v_mov_b32_e32 v106, v0
	v_mov_b32_e32 v107, v0
	v_mov_b32_e32 v116, v0
	v_mov_b32_e32 v117, v0
	v_mov_b32_e32 v118, v0
	v_mov_b32_e32 v119, v0
	v_mov_b32_e32 v120, v0
	v_mov_b32_e32 v121, v0
	v_mov_b32_e32 v122, v0
	v_mov_b32_e32 v123, v0
	v_mov_b32_e32 v124, v0
	v_mov_b32_e32 v125, v0
	v_mov_b32_e32 v126, v0
	v_mov_b32_e32 v127, v0
.LBB0_1167:
	ds_read_b128 v[148:151], v143
	ds_read_b128 v[152:155], v143 offset:1024
	ds_read_b128 v[156:159], v143 offset:2048
	ds_read_b128 v[160:163], v143 offset:3072
	s_add_u32 s24, s22, 0xfff80080
	s_addc_u32 s25, s23, -1
	s_cmp_eq_u32 s53, 28
	s_cselect_b32 s27, s15, s25
	s_cselect_b32 s26, s49, s24
	s_cselect_b32 s25, s13, s52
	s_cselect_b32 s24, s50, s51
	v_lshl_add_u64 v[136:137], s[22:23], 0, v[128:129]
	s_add_i32 m0, s21, 0xc000
	ds_read_b128 v[164:167], v145
	ds_read_b128 v[176:179], v145 offset:1024
	ds_read_b128 v[180:183], v145 offset:2048
	ds_read_b128 v[184:187], v145 offset:3072
	ds_read_b128 v[188:191], v145 offset:4096
	ds_read_b128 v[192:195], v145 offset:5120
	ds_read_b128 v[196:199], v145 offset:6144
	ds_read_b128 v[200:203], v145 offset:7168
	global_load_lds_dwordx4 v[136:137], off
	v_lshl_add_u64 v[136:137], s[22:23], 0, v[130:131]
	s_add_i32 m0, s21, 0xe000
	s_nop 0
	global_load_lds_dwordx4 v[136:137], off
	s_waitcnt lgkmcnt(8)
	s_barrier
	s_waitcnt lgkmcnt(0)
	s_setprio 1
	s_waitcnt lgkmcnt(0)
	v_mfma_f32_16x16x32_bf16 v[124:127], v[148:151], v[164:167], v[124:127]
	v_mfma_f32_16x16x32_bf16 v[120:123], v[156:159], v[164:167], v[120:123]
	v_mfma_f32_16x16x32_bf16 v[116:119], v[148:151], v[180:183], v[116:119]
	v_mfma_f32_16x16x32_bf16 v[104:107], v[156:159], v[180:183], v[104:107]
	v_mfma_f32_16x16x32_bf16 v[96:99], v[148:151], v[188:191], v[96:99]
	v_mfma_f32_16x16x32_bf16 v[88:91], v[156:159], v[188:191], v[88:91]
	v_mfma_f32_16x16x32_bf16 v[80:83], v[148:151], v[196:199], v[80:83]
	v_mfma_f32_16x16x32_bf16 v[72:75], v[156:159], v[196:199], v[72:75]
	v_mfma_f32_16x16x32_bf16 v[124:127], v[152:155], v[176:179], v[124:127]
	v_mfma_f32_16x16x32_bf16 v[120:123], v[160:163], v[176:179], v[120:123]
	v_mfma_f32_16x16x32_bf16 v[116:119], v[152:155], v[184:187], v[116:119]
	v_mfma_f32_16x16x32_bf16 v[104:107], v[160:163], v[184:187], v[104:107]
	v_mfma_f32_16x16x32_bf16 v[96:99], v[152:155], v[192:195], v[96:99]
	v_mfma_f32_16x16x32_bf16 v[88:91], v[160:163], v[192:195], v[88:91]
	v_mfma_f32_16x16x32_bf16 v[80:83], v[152:155], v[200:203], v[80:83]
	v_mfma_f32_16x16x32_bf16 v[72:75], v[160:163], v[200:203], v[72:75]
	s_setprio 0
	s_barrier
	s_add_i32 s54, s45, s31
	v_lshl_add_u64 v[136:137], s[24:25], 0, v[172:173]
	s_mov_b32 m0, s54
	ds_read_b128 v[204:207], v147
	ds_read_b128 v[218:221], v147 offset:1024
	ds_read_b128 v[222:225], v147 offset:2048
	ds_read_b128 v[226:229], v147 offset:3072
	global_load_lds_dwordx4 v[136:137], off
	v_lshl_add_u64 v[140:141], s[24:25], 0, v[174:175]
	s_add_i32 m0, s54, 0x2000
	s_nop 0
	global_load_lds_dwordx4 v[140:141], off
	s_barrier
	s_waitcnt lgkmcnt(0)
	s_setprio 1
	s_waitcnt lgkmcnt(0)
	v_mfma_f32_16x16x32_bf16 v[112:115], v[204:207], v[164:167], v[112:115]
	v_mfma_f32_16x16x32_bf16 v[108:111], v[222:225], v[164:167], v[108:111]
	v_mfma_f32_16x16x32_bf16 v[100:103], v[204:207], v[180:183], v[100:103]
	v_mfma_f32_16x16x32_bf16 v[92:95], v[222:225], v[180:183], v[92:95]
	v_mfma_f32_16x16x32_bf16 v[84:87], v[204:207], v[188:191], v[84:87]
	v_mfma_f32_16x16x32_bf16 v[76:79], v[222:225], v[188:191], v[76:79]
	v_mfma_f32_16x16x32_bf16 v[68:71], v[204:207], v[196:199], v[68:71]
	v_mfma_f32_16x16x32_bf16 v[64:67], v[222:225], v[196:199], v[64:67]
	v_mfma_f32_16x16x32_bf16 v[112:115], v[218:221], v[176:179], v[112:115]
	v_mfma_f32_16x16x32_bf16 v[108:111], v[226:229], v[176:179], v[108:111]
	v_mfma_f32_16x16x32_bf16 v[100:103], v[218:221], v[184:187], v[100:103]
	v_mfma_f32_16x16x32_bf16 v[92:95], v[226:229], v[184:187], v[92:95]
	v_mfma_f32_16x16x32_bf16 v[84:87], v[218:221], v[192:195], v[84:87]
	v_mfma_f32_16x16x32_bf16 v[76:79], v[226:229], v[192:195], v[76:79]
	v_mfma_f32_16x16x32_bf16 v[68:71], v[218:221], v[200:203], v[68:71]
	v_mfma_f32_16x16x32_bf16 v[64:67], v[226:229], v[200:203], v[64:67]
	s_setprio 0
	s_mov_b32 m0, s21
	v_lshl_add_u64 v[208:209], s[26:27], 0, v[172:173]
	s_barrier
	ds_read_b128 v[164:167], v145 offset:16384
	ds_read_b128 v[176:179], v145 offset:17408
	ds_read_b128 v[180:183], v145 offset:18432
	ds_read_b128 v[184:187], v145 offset:19456
	ds_read_b128 v[188:191], v145 offset:20480
	ds_read_b128 v[192:195], v145 offset:21504
	ds_read_b128 v[196:199], v145 offset:22528
	ds_read_b128 v[200:203], v145 offset:23552
	global_load_lds_dwordx4 v[208:209], off
	v_lshl_add_u64 v[230:231], s[26:27], 0, v[174:175]
	s_mov_b32 m0, s35
	s_nop 0
	global_load_lds_dwordx4 v[230:231], off
	s_barrier
	s_waitcnt lgkmcnt(0)
	s_setprio 1
	s_waitcnt lgkmcnt(0)
	v_mfma_f32_16x16x32_bf16 v[60:63], v[148:151], v[164:167], v[60:63]
	v_mfma_f32_16x16x32_bf16 v[56:59], v[156:159], v[164:167], v[56:59]
	v_mfma_f32_16x16x32_bf16 v[48:51], v[148:151], v[180:183], v[48:51]
	v_mfma_f32_16x16x32_bf16 v[40:43], v[156:159], v[180:183], v[40:43]
	v_mfma_f32_16x16x32_bf16 v[32:35], v[148:151], v[188:191], v[32:35]
	v_mfma_f32_16x16x32_bf16 v[24:27], v[156:159], v[188:191], v[24:27]
	v_mfma_f32_16x16x32_bf16 v[16:19], v[148:151], v[196:199], v[16:19]
	v_mfma_f32_16x16x32_bf16 v[8:11], v[156:159], v[196:199], v[8:11]
	v_mfma_f32_16x16x32_bf16 v[60:63], v[152:155], v[176:179], v[60:63]
	v_mfma_f32_16x16x32_bf16 v[56:59], v[160:163], v[176:179], v[56:59]
	v_mfma_f32_16x16x32_bf16 v[48:51], v[152:155], v[184:187], v[48:51]
	v_mfma_f32_16x16x32_bf16 v[40:43], v[160:163], v[184:187], v[40:43]
	v_mfma_f32_16x16x32_bf16 v[32:35], v[152:155], v[192:195], v[32:35]
	v_mfma_f32_16x16x32_bf16 v[24:27], v[160:163], v[192:195], v[24:27]
	v_mfma_f32_16x16x32_bf16 v[16:19], v[152:155], v[200:203], v[16:19]
	v_mfma_f32_16x16x32_bf16 v[8:11], v[160:163], v[200:203], v[8:11]
	s_setprio 0
	s_barrier
	s_add_u32 s54, s24, 0x80000
	s_addc_u32 s55, s25, 0
	s_add_i32 s56, s46, s31
	v_lshl_add_u64 v[148:149], s[54:55], 0, v[172:173]
	s_mov_b32 m0, s56
	s_nop 0
	global_load_lds_dwordx4 v[148:149], off
	v_lshl_add_u64 v[148:149], s[54:55], 0, v[174:175]
	s_add_i32 m0, s56, 0x2000
	s_nop 0
	global_load_lds_dwordx4 v[148:149], off
	s_waitcnt vmcnt(6)
	s_barrier
	s_setprio 1
	v_mfma_f32_16x16x32_bf16 v[52:55], v[204:207], v[164:167], v[52:55]
	v_mfma_f32_16x16x32_bf16 v[44:47], v[222:225], v[164:167], v[44:47]
	v_mfma_f32_16x16x32_bf16 v[36:39], v[204:207], v[180:183], v[36:39]
	v_mfma_f32_16x16x32_bf16 v[28:31], v[222:225], v[180:183], v[28:31]
	v_mfma_f32_16x16x32_bf16 v[20:23], v[204:207], v[188:191], v[20:23]
	v_mfma_f32_16x16x32_bf16 v[12:15], v[222:225], v[188:191], v[12:15]
	v_mfma_f32_16x16x32_bf16 v[4:7], v[204:207], v[196:199], v[4:7]
	v_mfma_f32_16x16x32_bf16 v[0:3], v[222:225], v[196:199], v[0:3]
	v_mfma_f32_16x16x32_bf16 v[52:55], v[218:221], v[176:179], v[52:55]
	v_mfma_f32_16x16x32_bf16 v[44:47], v[226:229], v[176:179], v[44:47]
	v_mfma_f32_16x16x32_bf16 v[36:39], v[218:221], v[184:187], v[36:39]
	v_mfma_f32_16x16x32_bf16 v[28:31], v[226:229], v[184:187], v[28:31]
	v_mfma_f32_16x16x32_bf16 v[20:23], v[218:221], v[192:195], v[20:23]
	v_mfma_f32_16x16x32_bf16 v[12:15], v[226:229], v[192:195], v[12:15]
	v_mfma_f32_16x16x32_bf16 v[4:7], v[218:221], v[200:203], v[4:7]
	v_mfma_f32_16x16x32_bf16 v[0:3], v[226:229], v[200:203], v[0:3]
	s_setprio 0
	s_add_i32 s54, 0, 0x18000
	v_add_u32_e32 v138, s54, v139
	s_barrier
	ds_read_b128 v[148:151], v138
	ds_read_b128 v[152:155], v138 offset:1024
	ds_read_b128 v[156:159], v138 offset:2048
	ds_read_b128 v[160:163], v138 offset:3072
	s_add_u32 s26, s26, 0x80000
	s_addc_u32 s27, s27, 0
	s_mov_b32 m0, s36
	v_lshl_add_u64 v[204:205], s[26:27], 0, v[172:173]
	ds_read_b128 v[164:167], v145 offset:32768
	ds_read_b128 v[176:179], v145 offset:33792
	ds_read_b128 v[180:183], v145 offset:34816
	ds_read_b128 v[184:187], v145 offset:35840
	ds_read_b128 v[188:191], v145 offset:36864
	ds_read_b128 v[192:195], v145 offset:37888
	ds_read_b128 v[196:199], v145 offset:38912
	ds_read_b128 v[200:203], v145 offset:39936
	global_load_lds_dwordx4 v[204:205], off
	v_lshl_add_u64 v[204:205], s[26:27], 0, v[174:175]
	s_mov_b32 m0, s37
	s_nop 0
	global_load_lds_dwordx4 v[204:205], off
	s_waitcnt lgkmcnt(8)
	s_barrier
	s_waitcnt lgkmcnt(0)
	s_setprio 1
	s_waitcnt lgkmcnt(0)
	v_mfma_f32_16x16x32_bf16 v[124:127], v[148:151], v[164:167], v[124:127]
	v_mfma_f32_16x16x32_bf16 v[120:123], v[156:159], v[164:167], v[120:123]
	v_mfma_f32_16x16x32_bf16 v[116:119], v[148:151], v[180:183], v[116:119]
	v_mfma_f32_16x16x32_bf16 v[104:107], v[156:159], v[180:183], v[104:107]
	v_mfma_f32_16x16x32_bf16 v[96:99], v[148:151], v[188:191], v[96:99]
	v_mfma_f32_16x16x32_bf16 v[88:91], v[156:159], v[188:191], v[88:91]
	v_mfma_f32_16x16x32_bf16 v[80:83], v[148:151], v[196:199], v[80:83]
	v_mfma_f32_16x16x32_bf16 v[72:75], v[156:159], v[196:199], v[72:75]
	v_mfma_f32_16x16x32_bf16 v[124:127], v[152:155], v[176:179], v[124:127]
	v_mfma_f32_16x16x32_bf16 v[120:123], v[160:163], v[176:179], v[120:123]
	v_mfma_f32_16x16x32_bf16 v[116:119], v[152:155], v[184:187], v[116:119]
	v_mfma_f32_16x16x32_bf16 v[104:107], v[160:163], v[184:187], v[104:107]
	v_mfma_f32_16x16x32_bf16 v[96:99], v[152:155], v[192:195], v[96:99]
	v_mfma_f32_16x16x32_bf16 v[88:91], v[160:163], v[192:195], v[88:91]
	v_mfma_f32_16x16x32_bf16 v[80:83], v[152:155], v[200:203], v[80:83]
	v_mfma_f32_16x16x32_bf16 v[72:75], v[160:163], v[200:203], v[72:75]
	s_setprio 0
	s_barrier
	s_add_i32 s26, 0, 0x1c000
	s_add_i32 s27, s54, s31
	v_add_u32_e32 v138, s26, v139
	v_lshl_add_u64 v[136:137], v[136:137], 0, s[10:11]
	s_mov_b32 m0, s27
	ds_read_b128 v[204:207], v138
	ds_read_b128 v[218:221], v138 offset:1024
	ds_read_b128 v[222:225], v138 offset:2048
	ds_read_b128 v[226:229], v138 offset:3072
	global_load_lds_dwordx4 v[136:137], off
	v_lshl_add_u64 v[136:137], v[140:141], 0, s[10:11]
	s_add_i32 m0, s27, 0x2000
	s_nop 0
	global_load_lds_dwordx4 v[136:137], off
	s_barrier
	s_waitcnt lgkmcnt(0)
	s_setprio 1
	s_waitcnt lgkmcnt(0)
	v_mfma_f32_16x16x32_bf16 v[112:115], v[204:207], v[164:167], v[112:115]
	v_mfma_f32_16x16x32_bf16 v[108:111], v[222:225], v[164:167], v[108:111]
	v_mfma_f32_16x16x32_bf16 v[100:103], v[204:207], v[180:183], v[100:103]
	v_mfma_f32_16x16x32_bf16 v[92:95], v[222:225], v[180:183], v[92:95]
	v_mfma_f32_16x16x32_bf16 v[84:87], v[204:207], v[188:191], v[84:87]
	v_mfma_f32_16x16x32_bf16 v[76:79], v[222:225], v[188:191], v[76:79]
	v_mfma_f32_16x16x32_bf16 v[68:71], v[204:207], v[196:199], v[68:71]
	v_mfma_f32_16x16x32_bf16 v[64:67], v[222:225], v[196:199], v[64:67]
	v_mfma_f32_16x16x32_bf16 v[112:115], v[218:221], v[176:179], v[112:115]
	v_mfma_f32_16x16x32_bf16 v[108:111], v[226:229], v[176:179], v[108:111]
	v_mfma_f32_16x16x32_bf16 v[100:103], v[218:221], v[184:187], v[100:103]
	v_mfma_f32_16x16x32_bf16 v[92:95], v[226:229], v[184:187], v[92:95]
	v_mfma_f32_16x16x32_bf16 v[84:87], v[218:221], v[192:195], v[84:87]
	v_mfma_f32_16x16x32_bf16 v[76:79], v[226:229], v[192:195], v[76:79]
	v_mfma_f32_16x16x32_bf16 v[68:71], v[218:221], v[200:203], v[68:71]
	v_mfma_f32_16x16x32_bf16 v[64:67], v[226:229], v[200:203], v[64:67]
	s_setprio 0
	s_mov_b32 m0, s41
	v_lshl_add_u64 v[136:137], v[208:209], 0, s[10:11]
	s_barrier
	ds_read_b128 v[164:167], v145 offset:49152
	ds_read_b128 v[176:179], v145 offset:50176
	ds_read_b128 v[180:183], v145 offset:51200
	ds_read_b128 v[184:187], v145 offset:52224
	ds_read_b128 v[188:191], v145 offset:53248
	ds_read_b128 v[192:195], v145 offset:54272
	ds_read_b128 v[196:199], v145 offset:55296
	ds_read_b128 v[200:203], v145 offset:56320
	global_load_lds_dwordx4 v[136:137], off
	v_lshl_add_u64 v[136:137], v[230:231], 0, s[10:11]
	s_mov_b32 m0, s42
	s_nop 0
	global_load_lds_dwordx4 v[136:137], off
	s_barrier
	s_waitcnt lgkmcnt(0)
	s_setprio 1
	s_waitcnt lgkmcnt(0)
	v_mfma_f32_16x16x32_bf16 v[60:63], v[148:151], v[164:167], v[60:63]
	v_mfma_f32_16x16x32_bf16 v[56:59], v[156:159], v[164:167], v[56:59]
	v_mfma_f32_16x16x32_bf16 v[48:51], v[148:151], v[180:183], v[48:51]
	v_mfma_f32_16x16x32_bf16 v[40:43], v[156:159], v[180:183], v[40:43]
	v_mfma_f32_16x16x32_bf16 v[32:35], v[148:151], v[188:191], v[32:35]
	v_mfma_f32_16x16x32_bf16 v[24:27], v[156:159], v[188:191], v[24:27]
	v_mfma_f32_16x16x32_bf16 v[16:19], v[148:151], v[196:199], v[16:19]
	v_mfma_f32_16x16x32_bf16 v[8:11], v[156:159], v[196:199], v[8:11]
	v_mfma_f32_16x16x32_bf16 v[60:63], v[152:155], v[176:179], v[60:63]
	v_mfma_f32_16x16x32_bf16 v[56:59], v[160:163], v[176:179], v[56:59]
	v_mfma_f32_16x16x32_bf16 v[48:51], v[152:155], v[184:187], v[48:51]
	v_mfma_f32_16x16x32_bf16 v[40:43], v[160:163], v[184:187], v[40:43]
	v_mfma_f32_16x16x32_bf16 v[32:35], v[152:155], v[192:195], v[32:35]
	v_mfma_f32_16x16x32_bf16 v[24:27], v[160:163], v[192:195], v[24:27]
	v_mfma_f32_16x16x32_bf16 v[16:19], v[152:155], v[200:203], v[16:19]
	v_mfma_f32_16x16x32_bf16 v[8:11], v[160:163], v[200:203], v[8:11]
	s_setprio 0
	s_barrier
	s_add_u32 s24, s24, 0x80080
	s_addc_u32 s25, s25, 0
	s_add_i32 s26, s26, s31
	v_lshl_add_u64 v[136:137], s[24:25], 0, v[172:173]
	s_mov_b32 m0, s26
	s_nop 0
	global_load_lds_dwordx4 v[136:137], off
	v_lshl_add_u64 v[136:137], s[24:25], 0, v[174:175]
	s_add_i32 m0, s26, 0x2000
	s_nop 0
	global_load_lds_dwordx4 v[136:137], off
	s_waitcnt vmcnt(6)
	s_barrier
	s_setprio 1
	v_mfma_f32_16x16x32_bf16 v[52:55], v[204:207], v[164:167], v[52:55]
	v_mfma_f32_16x16x32_bf16 v[44:47], v[222:225], v[164:167], v[44:47]
	v_mfma_f32_16x16x32_bf16 v[36:39], v[204:207], v[180:183], v[36:39]
	v_mfma_f32_16x16x32_bf16 v[28:31], v[222:225], v[180:183], v[28:31]
	v_mfma_f32_16x16x32_bf16 v[20:23], v[204:207], v[188:191], v[20:23]
	v_mfma_f32_16x16x32_bf16 v[12:15], v[222:225], v[188:191], v[12:15]
	v_mfma_f32_16x16x32_bf16 v[4:7], v[204:207], v[196:199], v[4:7]
	v_mfma_f32_16x16x32_bf16 v[0:3], v[222:225], v[196:199], v[0:3]
	v_mfma_f32_16x16x32_bf16 v[52:55], v[218:221], v[176:179], v[52:55]
	v_mfma_f32_16x16x32_bf16 v[44:47], v[226:229], v[176:179], v[44:47]
	v_mfma_f32_16x16x32_bf16 v[36:39], v[218:221], v[184:187], v[36:39]
	v_mfma_f32_16x16x32_bf16 v[28:31], v[226:229], v[184:187], v[28:31]
	v_mfma_f32_16x16x32_bf16 v[20:23], v[218:221], v[192:195], v[20:23]
	v_mfma_f32_16x16x32_bf16 v[12:15], v[226:229], v[192:195], v[12:15]
	v_mfma_f32_16x16x32_bf16 v[4:7], v[218:221], v[200:203], v[4:7]
	v_mfma_f32_16x16x32_bf16 v[0:3], v[226:229], v[200:203], v[0:3]
	s_setprio 0
	s_add_i32 s53, s53, 2
	s_add_u32 s22, s22, 0x100
	s_addc_u32 s23, s23, 0
	s_add_u32 s51, s51, 0x100
	s_addc_u32 s52, s52, 0
	s_cmp_gt_u32 s53, 29
	s_barrier
	s_cbranch_scc0 .LBB0_1167
	s_lshl_b32 s13, s20, 8
	v_mov_b32_e32 v138, v210
	v_mov_b32_e32 v142, v169
	s_add_i32 s13, s13, s39
	s_lshl_b32 s15, s48, 7
	v_add_u32_e32 v136, s13, v142
	v_ashrrev_i32_e32 v137, 31, v136
	v_lshl_add_u64 v[140:141], v[136:137], 2, s[2:3]
	v_mov_b32_e32 v154, v232
	v_mov_b32_e32 v152, v233
	v_lshl_add_u32 v138, v138, 4, v142
	v_and_b32_e32 v142, 3, v142
	v_ashrrev_i32_e32 v144, 2, v138
	v_and_b32_e32 v138, -4, v138
	v_lshl_or_b32 v146, v142, 2, s15
	v_add_u32_e32 v151, s13, v144
	v_lshl_add_u32 v149, v142, 6, v138
	v_or_b32_e32 v156, s40, v146
	v_mov_b32_e32 v150, v234
	v_mov_b32_e32 v148, v235
	v_mov_b32_e32 v146, v236
	v_mov_b32_e32 v144, v237
	v_mov_b32_e32 v142, v238
	v_mov_b32_e32 v138, v239
	v_mov_b64_e32 v[136:137], s[0:1]
	v_ashrrev_i32_e32 v157, 31, v156
	v_mad_i64_i32 v[158:159], s[22:23], v151, s47, v[136:137]
	v_lshlrev_b64 v[140:141], 1, v[156:157]
	v_lshl_add_u64 v[156:157], v[158:159], 0, v[140:141]
	v_add_u32_e32 v153, 16, v151
	s_and_b64 vcc, exec, s[4:5]
	s_mov_b32 s48, s12
	s_mov_b32 s20, s14
	s_mov_b64 s[24:25], s[18:19]
	s_nop 0
	v_pk_mul_f32 v[126:127], v[126:127], v[154:155] op_sel_hi:[1,0]
	v_pk_mul_f32 v[124:125], v[124:125], v[154:155] op_sel_hi:[1,0]
	v_pk_mul_f32 v[114:115], v[114:115], v[154:155] op_sel_hi:[1,0]
	v_pk_mul_f32 v[112:113], v[112:113], v[154:155] op_sel_hi:[1,0]
	v_pk_mul_f32 v[122:123], v[122:123], v[154:155] op_sel_hi:[1,0]
	v_pk_mul_f32 v[120:121], v[120:121], v[154:155] op_sel_hi:[1,0]
	v_pk_mul_f32 v[110:111], v[110:111], v[154:155] op_sel_hi:[1,0]
	v_pk_mul_f32 v[108:109], v[108:109], v[154:155] op_sel_hi:[1,0]
	v_mul_f32_e32 v154, 0xbfb8aa3b, v124
	v_mul_f32_e32 v155, 0xbfb8aa3b, v125
	v_mul_f32_e32 v158, 0xbfb8aa3b, v126
	v_mul_f32_e32 v159, 0xbfb8aa3b, v127
	v_mul_f32_e32 v160, 0xbfb8aa3b, v120
	v_mul_f32_e32 v161, 0xbfb8aa3b, v121
	v_mul_f32_e32 v162, 0xbfb8aa3b, v122
	v_mul_f32_e32 v163, 0xbfb8aa3b, v123
	v_exp_f32_e32 v154, v154
	v_exp_f32_e32 v155, v155
	v_exp_f32_e32 v158, v158
	v_exp_f32_e32 v159, v159
	v_exp_f32_e32 v160, v160
	v_exp_f32_e32 v161, v161
	v_exp_f32_e32 v162, v162
	v_exp_f32_e32 v163, v163
	v_add_f32_e32 v154, 1.0, v154
	v_add_f32_e32 v155, 1.0, v155
	v_add_f32_e32 v158, 1.0, v158
	v_add_f32_e32 v159, 1.0, v159
	v_add_f32_e32 v160, 1.0, v160
	v_add_f32_e32 v161, 1.0, v161
	v_add_f32_e32 v162, 1.0, v162
	v_add_f32_e32 v163, 1.0, v163
	v_rcp_f32_e32 v154, v154
	v_rcp_f32_e32 v155, v155
	v_rcp_f32_e32 v158, v158
	v_rcp_f32_e32 v159, v159
	v_rcp_f32_e32 v160, v160
	v_rcp_f32_e32 v161, v161
	v_rcp_f32_e32 v162, v162
	v_rcp_f32_e32 v163, v163
	v_pk_mul_f32 v[124:125], v[124:125], v[154:155]
	v_pk_mul_f32 v[126:127], v[126:127], v[158:159]
	v_pk_mul_f32 v[120:121], v[120:121], v[160:161]
	v_pk_mul_f32 v[122:123], v[122:123], v[162:163]
	v_pk_mul_f32 v[112:113], v[112:113], v[124:125]
	v_pk_mul_f32 v[114:115], v[114:115], v[126:127]
	v_pk_mul_f32 v[118:119], v[118:119], v[152:153] op_sel_hi:[1,0]
	v_pk_mul_f32 v[116:117], v[116:117], v[152:153] op_sel_hi:[1,0]
	v_pk_mul_f32 v[108:109], v[108:109], v[120:121]
	v_pk_mul_f32 v[110:111], v[110:111], v[122:123]
	v_cvt_pk_bf16_f32 v112, v112, v113
	v_cvt_pk_bf16_f32 v113, v114, v115
	v_mul_f32_e32 v164, 0xbfb8aa3b, v116
	v_mul_f32_e32 v165, 0xbfb8aa3b, v117
	v_mul_f32_e32 v166, 0xbfb8aa3b, v118
	v_mul_f32_e32 v167, 0xbfb8aa3b, v119
	v_cvt_pk_bf16_f32 v114, v108, v109
	v_cvt_pk_bf16_f32 v111, v110, v111
	ds_bpermute_b32 v108, v149, v112
	ds_bpermute_b32 v109, v149, v113
	v_exp_f32_e32 v164, v164
	v_exp_f32_e32 v165, v165
	v_exp_f32_e32 v166, v166
	v_exp_f32_e32 v167, v167
	ds_bpermute_b32 v110, v149, v114
	ds_bpermute_b32 v111, v149, v111
	v_add_f32_e32 v164, 1.0, v164
	v_add_f32_e32 v113, 1.0, v165
	s_waitcnt lgkmcnt(0)
	global_store_dwordx2 v[156:157], v[108:109], off
	global_store_dwordx2 v[156:157], v[110:111], off offset:32
	v_add_f32_e32 v108, 1.0, v166
	v_add_f32_e32 v109, 1.0, v167
	v_rcp_f32_e32 v112, v164
	v_rcp_f32_e32 v113, v113
	v_rcp_f32_e32 v108, v108
	v_rcp_f32_e32 v109, v109
	v_pk_mul_f32 v[102:103], v[102:103], v[152:153] op_sel_hi:[1,0]
	v_pk_mul_f32 v[100:101], v[100:101], v[152:153] op_sel_hi:[1,0]
	v_pk_mul_f32 v[110:111], v[116:117], v[112:113]
	v_pk_mul_f32 v[108:109], v[118:119], v[108:109]
	v_pk_mul_f32 v[100:101], v[100:101], v[110:111]
	v_pk_mul_f32 v[102:103], v[102:103], v[108:109]
	v_cvt_pk_bf16_f32 v100, v100, v101
	v_cvt_pk_bf16_f32 v101, v102, v103
	v_pk_mul_f32 v[102:103], v[106:107], v[152:153] op_sel_hi:[1,0]
	v_pk_mul_f32 v[104:105], v[104:105], v[152:153] op_sel_hi:[1,0]
	v_mul_f32_e32 v108, 0xbfb8aa3b, v102
	v_mul_f32_e32 v106, 0xbfb8aa3b, v104
	v_mul_f32_e32 v107, 0xbfb8aa3b, v105
	v_mul_f32_e32 v109, 0xbfb8aa3b, v103
	v_exp_f32_e32 v106, v106
	v_exp_f32_e32 v107, v107
	v_exp_f32_e32 v108, v108
	v_exp_f32_e32 v109, v109
	v_add_f32_e32 v106, 1.0, v106
	v_add_f32_e32 v107, 1.0, v107
	v_add_f32_e32 v108, 1.0, v108
	v_add_f32_e32 v109, 1.0, v109
	v_rcp_f32_e32 v106, v106
	v_rcp_f32_e32 v107, v107
	v_rcp_f32_e32 v108, v108
	v_rcp_f32_e32 v109, v109
	v_pk_mul_f32 v[94:95], v[94:95], v[152:153] op_sel_hi:[1,0]
	v_pk_mul_f32 v[92:93], v[92:93], v[152:153] op_sel_hi:[1,0]
	v_pk_mul_f32 v[104:105], v[104:105], v[106:107]
	v_pk_mul_f32 v[102:103], v[102:103], v[108:109]
	v_pk_mul_f32 v[92:93], v[92:93], v[104:105]
	v_pk_mul_f32 v[94:95], v[94:95], v[102:103]
	ds_bpermute_b32 v100, v149, v100
	ds_bpermute_b32 v101, v149, v101
	v_cvt_pk_bf16_f32 v92, v92, v93
	v_cvt_pk_bf16_f32 v93, v94, v95
	ds_bpermute_b32 v92, v149, v92
	ds_bpermute_b32 v93, v149, v93
	v_mad_i64_i32 v[94:95], s[22:23], v153, s47, v[136:137]
	v_lshl_add_u64 v[94:95], v[94:95], 0, v[140:141]
	s_waitcnt lgkmcnt(2)
	global_store_dwordx2 v[94:95], v[100:101], off
	s_waitcnt lgkmcnt(0)
	global_store_dwordx2 v[94:95], v[92:93], off offset:32
	v_pk_mul_f32 v[92:93], v[98:99], v[150:151] op_sel_hi:[1,0]
	v_pk_mul_f32 v[94:95], v[96:97], v[150:151] op_sel_hi:[1,0]
	v_mul_f32_e32 v98, 0xbfb8aa3b, v92
	v_mul_f32_e32 v96, 0xbfb8aa3b, v94
	v_mul_f32_e32 v97, 0xbfb8aa3b, v95
	v_mul_f32_e32 v99, 0xbfb8aa3b, v93
	v_exp_f32_e32 v96, v96
	v_exp_f32_e32 v97, v97
	v_exp_f32_e32 v98, v98
	v_exp_f32_e32 v99, v99
	v_add_f32_e32 v96, 1.0, v96
	v_add_f32_e32 v97, 1.0, v97
	v_add_f32_e32 v98, 1.0, v98
	v_add_f32_e32 v99, 1.0, v99
	v_rcp_f32_e32 v96, v96
	v_rcp_f32_e32 v97, v97
	v_rcp_f32_e32 v98, v98
	v_rcp_f32_e32 v99, v99
	v_pk_mul_f32 v[86:87], v[86:87], v[150:151] op_sel_hi:[1,0]
	v_pk_mul_f32 v[84:85], v[84:85], v[150:151] op_sel_hi:[1,0]
	v_pk_mul_f32 v[94:95], v[94:95], v[96:97]
	v_pk_mul_f32 v[92:93], v[92:93], v[98:99]
	v_pk_mul_f32 v[84:85], v[84:85], v[94:95]
	v_pk_mul_f32 v[86:87], v[86:87], v[92:93]
	v_cvt_pk_bf16_f32 v84, v84, v85
	v_cvt_pk_bf16_f32 v85, v86, v87
	v_pk_mul_f32 v[86:87], v[90:91], v[150:151] op_sel_hi:[1,0]
	v_pk_mul_f32 v[88:89], v[88:89], v[150:151] op_sel_hi:[1,0]
	v_mul_f32_e32 v92, 0xbfb8aa3b, v86
	v_mul_f32_e32 v90, 0xbfb8aa3b, v88
	v_mul_f32_e32 v91, 0xbfb8aa3b, v89
	v_mul_f32_e32 v93, 0xbfb8aa3b, v87
	v_exp_f32_e32 v90, v90
	v_exp_f32_e32 v91, v91
	v_exp_f32_e32 v92, v92
	v_exp_f32_e32 v93, v93
	v_add_f32_e32 v90, 1.0, v90
	v_add_f32_e32 v91, 1.0, v91
	v_add_f32_e32 v92, 1.0, v92
	v_add_f32_e32 v93, 1.0, v93
	v_rcp_f32_e32 v90, v90
	v_rcp_f32_e32 v91, v91
	v_rcp_f32_e32 v92, v92
	v_rcp_f32_e32 v93, v93
	v_pk_mul_f32 v[78:79], v[78:79], v[150:151] op_sel_hi:[1,0]
	v_pk_mul_f32 v[76:77], v[76:77], v[150:151] op_sel_hi:[1,0]
	v_pk_mul_f32 v[88:89], v[88:89], v[90:91]
	v_pk_mul_f32 v[86:87], v[86:87], v[92:93]
	v_pk_mul_f32 v[76:77], v[76:77], v[88:89]
	v_pk_mul_f32 v[78:79], v[78:79], v[86:87]
	ds_bpermute_b32 v84, v149, v84
	ds_bpermute_b32 v85, v149, v85
	v_cvt_pk_bf16_f32 v76, v76, v77
	v_cvt_pk_bf16_f32 v77, v78, v79
	ds_bpermute_b32 v76, v149, v76
	ds_bpermute_b32 v77, v149, v77
	v_add_u32_e32 v100, 32, v151
	v_mad_i64_i32 v[78:79], s[22:23], v100, s47, v[136:137]
	v_lshl_add_u64 v[78:79], v[78:79], 0, v[140:141]
	s_waitcnt lgkmcnt(2)
	global_store_dwordx2 v[78:79], v[84:85], off
	s_waitcnt lgkmcnt(0)
	global_store_dwordx2 v[78:79], v[76:77], off offset:32
	v_pk_mul_f32 v[76:77], v[82:83], v[148:149] op_sel_hi:[1,0]
	v_pk_mul_f32 v[78:79], v[80:81], v[148:149] op_sel_hi:[1,0]
	v_mul_f32_e32 v82, 0xbfb8aa3b, v76
	v_mul_f32_e32 v80, 0xbfb8aa3b, v78
	v_mul_f32_e32 v81, 0xbfb8aa3b, v79
	v_mul_f32_e32 v83, 0xbfb8aa3b, v77
	v_exp_f32_e32 v80, v80
	v_exp_f32_e32 v81, v81
	v_exp_f32_e32 v82, v82
	v_exp_f32_e32 v83, v83
	v_add_f32_e32 v80, 1.0, v80
	v_add_f32_e32 v81, 1.0, v81
	v_add_f32_e32 v82, 1.0, v82
	v_add_f32_e32 v83, 1.0, v83
	v_rcp_f32_e32 v80, v80
	v_rcp_f32_e32 v81, v81
	v_rcp_f32_e32 v82, v82
	v_rcp_f32_e32 v83, v83
	v_pk_mul_f32 v[70:71], v[70:71], v[148:149] op_sel_hi:[1,0]
	v_pk_mul_f32 v[68:69], v[68:69], v[148:149] op_sel_hi:[1,0]
	v_pk_mul_f32 v[78:79], v[78:79], v[80:81]
	v_pk_mul_f32 v[76:77], v[76:77], v[82:83]
	v_pk_mul_f32 v[68:69], v[68:69], v[78:79]
	v_pk_mul_f32 v[70:71], v[70:71], v[76:77]
	v_cvt_pk_bf16_f32 v68, v68, v69
	v_cvt_pk_bf16_f32 v69, v70, v71
	v_pk_mul_f32 v[70:71], v[74:75], v[148:149] op_sel_hi:[1,0]
	v_pk_mul_f32 v[72:73], v[72:73], v[148:149] op_sel_hi:[1,0]
	v_mul_f32_e32 v76, 0xbfb8aa3b, v70
	v_mul_f32_e32 v74, 0xbfb8aa3b, v72
	v_mul_f32_e32 v75, 0xbfb8aa3b, v73
	v_mul_f32_e32 v77, 0xbfb8aa3b, v71
	v_exp_f32_e32 v74, v74
	v_exp_f32_e32 v75, v75
	v_exp_f32_e32 v76, v76
	v_exp_f32_e32 v77, v77
	v_add_f32_e32 v74, 1.0, v74
	v_add_f32_e32 v75, 1.0, v75
	v_add_f32_e32 v76, 1.0, v76
	v_add_f32_e32 v77, 1.0, v77
	v_rcp_f32_e32 v74, v74
	v_rcp_f32_e32 v75, v75
	v_rcp_f32_e32 v76, v76
	v_rcp_f32_e32 v77, v77
	v_pk_mul_f32 v[66:67], v[66:67], v[148:149] op_sel_hi:[1,0]
	v_pk_mul_f32 v[64:65], v[64:65], v[148:149] op_sel_hi:[1,0]
	v_pk_mul_f32 v[72:73], v[72:73], v[74:75]
	v_pk_mul_f32 v[70:71], v[70:71], v[76:77]
	v_pk_mul_f32 v[64:65], v[64:65], v[72:73]
	v_pk_mul_f32 v[66:67], v[66:67], v[70:71]
	ds_bpermute_b32 v68, v149, v68
	ds_bpermute_b32 v69, v149, v69
	v_cvt_pk_bf16_f32 v64, v64, v65
	v_cvt_pk_bf16_f32 v65, v66, v67
	ds_bpermute_b32 v64, v149, v64
	ds_bpermute_b32 v65, v149, v65
	v_add_u32_e32 v84, 48, v151
	v_mad_i64_i32 v[66:67], s[22:23], v84, s47, v[136:137]
	v_lshl_add_u64 v[66:67], v[66:67], 0, v[140:141]
	v_pk_mul_f32 v[60:61], v[60:61], v[146:147] op_sel_hi:[1,0]
	s_waitcnt lgkmcnt(2)
	global_store_dwordx2 v[66:67], v[68:69], off
	s_waitcnt lgkmcnt(0)
	global_store_dwordx2 v[66:67], v[64:65], off offset:32
	v_pk_mul_f32 v[62:63], v[62:63], v[146:147] op_sel_hi:[1,0]
	v_mul_f32_e32 v64, 0xbfb8aa3b, v60
	v_mul_f32_e32 v65, 0xbfb8aa3b, v61
	v_exp_f32_e32 v64, v64
	v_exp_f32_e32 v65, v65
	v_mul_f32_e32 v66, 0xbfb8aa3b, v62
	v_mul_f32_e32 v67, 0xbfb8aa3b, v63
	v_exp_f32_e32 v66, v66
	v_exp_f32_e32 v67, v67
	v_add_f32_e32 v64, 1.0, v64
	v_add_f32_e32 v65, 1.0, v65
	v_rcp_f32_e32 v64, v64
	v_rcp_f32_e32 v65, v65
	v_add_f32_e32 v66, 1.0, v66
	v_add_f32_e32 v67, 1.0, v67
	v_rcp_f32_e32 v66, v66
	v_rcp_f32_e32 v67, v67
	v_pk_mul_f32 v[52:53], v[52:53], v[146:147] op_sel_hi:[1,0]
	v_pk_mul_f32 v[60:61], v[60:61], v[64:65]
	v_pk_mul_f32 v[54:55], v[54:55], v[146:147] op_sel_hi:[1,0]
	v_pk_mul_f32 v[52:53], v[52:53], v[60:61]
	v_pk_mul_f32 v[60:61], v[62:63], v[66:67]
	v_cvt_pk_bf16_f32 v52, v52, v53
	v_pk_mul_f32 v[54:55], v[54:55], v[60:61]
	v_pk_mul_f32 v[56:57], v[56:57], v[146:147] op_sel_hi:[1,0]
	v_cvt_pk_bf16_f32 v53, v54, v55
	v_pk_mul_f32 v[54:55], v[58:59], v[146:147] op_sel_hi:[1,0]
	v_mul_f32_e32 v58, 0xbfb8aa3b, v56
	v_mul_f32_e32 v59, 0xbfb8aa3b, v57
	v_mul_f32_e32 v60, 0xbfb8aa3b, v54
	v_mul_f32_e32 v61, 0xbfb8aa3b, v55
	v_exp_f32_e32 v58, v58
	v_exp_f32_e32 v59, v59
	v_exp_f32_e32 v60, v60
	v_exp_f32_e32 v61, v61
	v_add_f32_e32 v58, 1.0, v58
	v_add_f32_e32 v59, 1.0, v59
	v_add_f32_e32 v60, 1.0, v60
	v_add_f32_e32 v61, 1.0, v61
	v_rcp_f32_e32 v58, v58
	v_rcp_f32_e32 v59, v59
	v_rcp_f32_e32 v60, v60
	v_rcp_f32_e32 v61, v61
	v_pk_mul_f32 v[46:47], v[46:47], v[146:147] op_sel_hi:[1,0]
	v_pk_mul_f32 v[44:45], v[44:45], v[146:147] op_sel_hi:[1,0]
	v_pk_mul_f32 v[56:57], v[56:57], v[58:59]
	v_pk_mul_f32 v[54:55], v[54:55], v[60:61]
	v_pk_mul_f32 v[44:45], v[44:45], v[56:57]
	v_pk_mul_f32 v[46:47], v[46:47], v[54:55]
	ds_bpermute_b32 v52, v149, v52
	ds_bpermute_b32 v53, v149, v53
	v_cvt_pk_bf16_f32 v44, v44, v45
	v_cvt_pk_bf16_f32 v45, v46, v47
	ds_bpermute_b32 v44, v149, v44
	ds_bpermute_b32 v45, v149, v45
	v_add_u32_e32 v68, 0x80, v151
	v_mad_i64_i32 v[46:47], s[22:23], v68, s47, v[136:137]
	v_lshl_add_u64 v[46:47], v[46:47], 0, v[140:141]
	s_waitcnt lgkmcnt(2)
	global_store_dwordx2 v[46:47], v[52:53], off
	s_waitcnt lgkmcnt(0)
	global_store_dwordx2 v[46:47], v[44:45], off offset:32
	v_pk_mul_f32 v[44:45], v[50:51], v[144:145] op_sel_hi:[1,0]
	v_pk_mul_f32 v[46:47], v[48:49], v[144:145] op_sel_hi:[1,0]
	v_mul_f32_e32 v50, 0xbfb8aa3b, v44
	v_mul_f32_e32 v48, 0xbfb8aa3b, v46
	v_mul_f32_e32 v49, 0xbfb8aa3b, v47
	v_mul_f32_e32 v51, 0xbfb8aa3b, v45
	v_exp_f32_e32 v48, v48
	v_exp_f32_e32 v49, v49
	v_exp_f32_e32 v50, v50
	v_exp_f32_e32 v51, v51
	v_add_f32_e32 v48, 1.0, v48
	v_add_f32_e32 v49, 1.0, v49
	v_add_f32_e32 v50, 1.0, v50
	v_add_f32_e32 v51, 1.0, v51
	v_rcp_f32_e32 v48, v48
	v_rcp_f32_e32 v49, v49
	v_rcp_f32_e32 v50, v50
	v_rcp_f32_e32 v51, v51
	v_pk_mul_f32 v[38:39], v[38:39], v[144:145] op_sel_hi:[1,0]
	v_pk_mul_f32 v[36:37], v[36:37], v[144:145] op_sel_hi:[1,0]
	v_pk_mul_f32 v[46:47], v[46:47], v[48:49]
	v_pk_mul_f32 v[44:45], v[44:45], v[50:51]
	v_pk_mul_f32 v[36:37], v[36:37], v[46:47]
	v_pk_mul_f32 v[38:39], v[38:39], v[44:45]
	v_cvt_pk_bf16_f32 v36, v36, v37
	v_cvt_pk_bf16_f32 v37, v38, v39
	v_pk_mul_f32 v[38:39], v[42:43], v[144:145] op_sel_hi:[1,0]
	v_pk_mul_f32 v[40:41], v[40:41], v[144:145] op_sel_hi:[1,0]
	v_mul_f32_e32 v44, 0xbfb8aa3b, v38
	v_mul_f32_e32 v42, 0xbfb8aa3b, v40
	v_mul_f32_e32 v43, 0xbfb8aa3b, v41
	v_mul_f32_e32 v45, 0xbfb8aa3b, v39
	v_exp_f32_e32 v42, v42
	v_exp_f32_e32 v43, v43
	v_exp_f32_e32 v44, v44
	v_exp_f32_e32 v45, v45
	v_add_f32_e32 v42, 1.0, v42
	v_add_f32_e32 v43, 1.0, v43
	v_add_f32_e32 v44, 1.0, v44
	v_add_f32_e32 v45, 1.0, v45
	v_rcp_f32_e32 v42, v42
	v_rcp_f32_e32 v43, v43
	v_rcp_f32_e32 v44, v44
	v_rcp_f32_e32 v45, v45
	v_pk_mul_f32 v[30:31], v[30:31], v[144:145] op_sel_hi:[1,0]
	v_pk_mul_f32 v[28:29], v[28:29], v[144:145] op_sel_hi:[1,0]
	v_pk_mul_f32 v[40:41], v[40:41], v[42:43]
	v_pk_mul_f32 v[38:39], v[38:39], v[44:45]
	v_pk_mul_f32 v[28:29], v[28:29], v[40:41]
	v_pk_mul_f32 v[30:31], v[30:31], v[38:39]
	ds_bpermute_b32 v36, v149, v36
	ds_bpermute_b32 v37, v149, v37
	v_cvt_pk_bf16_f32 v28, v28, v29
	v_cvt_pk_bf16_f32 v29, v30, v31
	ds_bpermute_b32 v28, v149, v28
	ds_bpermute_b32 v29, v149, v29
	v_add_u32_e32 v52, 0x90, v151
	v_mad_i64_i32 v[30:31], s[22:23], v52, s47, v[136:137]
	v_lshl_add_u64 v[30:31], v[30:31], 0, v[140:141]
	s_waitcnt lgkmcnt(2)
	global_store_dwordx2 v[30:31], v[36:37], off
	s_waitcnt lgkmcnt(0)
	global_store_dwordx2 v[30:31], v[28:29], off offset:32
	v_pk_mul_f32 v[28:29], v[34:35], v[142:143] op_sel_hi:[1,0]
	v_pk_mul_f32 v[30:31], v[32:33], v[142:143] op_sel_hi:[1,0]
	v_mul_f32_e32 v34, 0xbfb8aa3b, v28
	v_mul_f32_e32 v32, 0xbfb8aa3b, v30
	v_mul_f32_e32 v33, 0xbfb8aa3b, v31
	v_mul_f32_e32 v35, 0xbfb8aa3b, v29
	v_exp_f32_e32 v32, v32
	v_exp_f32_e32 v33, v33
	v_exp_f32_e32 v34, v34
	v_exp_f32_e32 v35, v35
	v_add_f32_e32 v32, 1.0, v32
	v_add_f32_e32 v33, 1.0, v33
	v_add_f32_e32 v34, 1.0, v34
	v_add_f32_e32 v35, 1.0, v35
	v_rcp_f32_e32 v32, v32
	v_rcp_f32_e32 v33, v33
	v_rcp_f32_e32 v34, v34
	v_rcp_f32_e32 v35, v35
	v_pk_mul_f32 v[22:23], v[22:23], v[142:143] op_sel_hi:[1,0]
	v_pk_mul_f32 v[20:21], v[20:21], v[142:143] op_sel_hi:[1,0]
	v_pk_mul_f32 v[30:31], v[30:31], v[32:33]
	v_pk_mul_f32 v[28:29], v[28:29], v[34:35]
	v_pk_mul_f32 v[20:21], v[20:21], v[30:31]
	v_pk_mul_f32 v[22:23], v[22:23], v[28:29]
	v_cvt_pk_bf16_f32 v20, v20, v21
	v_cvt_pk_bf16_f32 v21, v22, v23
	v_pk_mul_f32 v[22:23], v[26:27], v[142:143] op_sel_hi:[1,0]
	v_pk_mul_f32 v[24:25], v[24:25], v[142:143] op_sel_hi:[1,0]
	v_mul_f32_e32 v28, 0xbfb8aa3b, v22
	v_mul_f32_e32 v26, 0xbfb8aa3b, v24
	v_mul_f32_e32 v27, 0xbfb8aa3b, v25
	v_mul_f32_e32 v29, 0xbfb8aa3b, v23
	v_exp_f32_e32 v26, v26
	v_exp_f32_e32 v27, v27
	v_exp_f32_e32 v28, v28
	v_exp_f32_e32 v29, v29
	v_add_f32_e32 v26, 1.0, v26
	v_add_f32_e32 v27, 1.0, v27
	v_add_f32_e32 v28, 1.0, v28
	v_add_f32_e32 v29, 1.0, v29
	v_rcp_f32_e32 v26, v26
	v_rcp_f32_e32 v27, v27
	v_rcp_f32_e32 v28, v28
	v_rcp_f32_e32 v29, v29
	v_pk_mul_f32 v[14:15], v[14:15], v[142:143] op_sel_hi:[1,0]
	v_pk_mul_f32 v[12:13], v[12:13], v[142:143] op_sel_hi:[1,0]
	v_pk_mul_f32 v[24:25], v[24:25], v[26:27]
	v_pk_mul_f32 v[22:23], v[22:23], v[28:29]
	v_pk_mul_f32 v[12:13], v[12:13], v[24:25]
	v_pk_mul_f32 v[14:15], v[14:15], v[22:23]
	ds_bpermute_b32 v20, v149, v20
	ds_bpermute_b32 v21, v149, v21
	v_cvt_pk_bf16_f32 v12, v12, v13
	v_cvt_pk_bf16_f32 v13, v14, v15
	ds_bpermute_b32 v12, v149, v12
	ds_bpermute_b32 v13, v149, v13
	v_add_u32_e32 v36, 0xa0, v151
	v_mad_i64_i32 v[14:15], s[22:23], v36, s47, v[136:137]
	v_lshl_add_u64 v[14:15], v[14:15], 0, v[140:141]
	s_waitcnt lgkmcnt(2)
	global_store_dwordx2 v[14:15], v[20:21], off
	s_waitcnt lgkmcnt(0)
	global_store_dwordx2 v[14:15], v[12:13], off offset:32
	v_pk_mul_f32 v[12:13], v[18:19], v[138:139] op_sel_hi:[1,0]
	v_pk_mul_f32 v[14:15], v[16:17], v[138:139] op_sel_hi:[1,0]
	v_mul_f32_e32 v18, 0xbfb8aa3b, v12
	v_mul_f32_e32 v16, 0xbfb8aa3b, v14
	v_mul_f32_e32 v17, 0xbfb8aa3b, v15
	v_mul_f32_e32 v19, 0xbfb8aa3b, v13
	v_exp_f32_e32 v16, v16
	v_exp_f32_e32 v17, v17
	v_exp_f32_e32 v18, v18
	v_exp_f32_e32 v19, v19
	v_add_f32_e32 v16, 1.0, v16
	v_add_f32_e32 v17, 1.0, v17
	v_add_f32_e32 v18, 1.0, v18
	v_add_f32_e32 v19, 1.0, v19
	v_rcp_f32_e32 v16, v16
	v_rcp_f32_e32 v17, v17
	v_rcp_f32_e32 v18, v18
	v_rcp_f32_e32 v19, v19
	v_pk_mul_f32 v[6:7], v[6:7], v[138:139] op_sel_hi:[1,0]
	v_pk_mul_f32 v[4:5], v[4:5], v[138:139] op_sel_hi:[1,0]
	v_pk_mul_f32 v[14:15], v[14:15], v[16:17]
	v_pk_mul_f32 v[12:13], v[12:13], v[18:19]
	v_pk_mul_f32 v[4:5], v[4:5], v[14:15]
	v_pk_mul_f32 v[6:7], v[6:7], v[12:13]
	v_cvt_pk_bf16_f32 v4, v4, v5
	v_cvt_pk_bf16_f32 v5, v6, v7
	v_pk_mul_f32 v[6:7], v[10:11], v[138:139] op_sel_hi:[1,0]
	v_pk_mul_f32 v[8:9], v[8:9], v[138:139] op_sel_hi:[1,0]
	v_mul_f32_e32 v12, 0xbfb8aa3b, v6
	v_mul_f32_e32 v10, 0xbfb8aa3b, v8
	v_mul_f32_e32 v11, 0xbfb8aa3b, v9
	v_mul_f32_e32 v13, 0xbfb8aa3b, v7
	v_exp_f32_e32 v10, v10
	v_exp_f32_e32 v11, v11
	v_exp_f32_e32 v12, v12
	v_exp_f32_e32 v13, v13
	v_add_f32_e32 v10, 1.0, v10
	v_add_f32_e32 v11, 1.0, v11
	v_add_f32_e32 v12, 1.0, v12
	v_add_f32_e32 v13, 1.0, v13
	v_rcp_f32_e32 v10, v10
	v_rcp_f32_e32 v11, v11
	v_rcp_f32_e32 v12, v12
	v_rcp_f32_e32 v13, v13
	v_pk_mul_f32 v[2:3], v[2:3], v[138:139] op_sel_hi:[1,0]
	v_pk_mul_f32 v[0:1], v[0:1], v[138:139] op_sel_hi:[1,0]
	v_pk_mul_f32 v[8:9], v[8:9], v[10:11]
	v_pk_mul_f32 v[6:7], v[6:7], v[12:13]
	v_pk_mul_f32 v[0:1], v[0:1], v[8:9]
	v_pk_mul_f32 v[2:3], v[2:3], v[6:7]
	ds_bpermute_b32 v4, v149, v4
	ds_bpermute_b32 v5, v149, v5
	v_cvt_pk_bf16_f32 v0, v0, v1
	v_cvt_pk_bf16_f32 v1, v2, v3
	ds_bpermute_b32 v0, v149, v0
	ds_bpermute_b32 v1, v149, v1
	v_add_u32_e32 v20, 0xb0, v151
	v_mad_i64_i32 v[2:3], s[22:23], v20, s47, v[136:137]
	v_lshl_add_u64 v[2:3], v[2:3], 0, v[140:141]
	s_mov_b64 s[22:23], s[16:17]
	s_waitcnt lgkmcnt(2)
	global_store_dwordx2 v[2:3], v[4:5], off
	s_waitcnt lgkmcnt(0)
	global_store_dwordx2 v[2:3], v[0:1], off offset:32
	s_cbranch_vccz .LBB0_1164
	s_waitcnt vmcnt(0)
	s_cmpk_gt_u32 s28, 0xff
	s_cbranch_scc1 .LBB0_1171
	s_barrier
